# A loop: the four tile LDS-DMA instructions per wave issued from MFMA gaps spread across the body instead of as a burst right after the barrier
# speedup vs baseline: 1.0767x; 1.0160x over previous
; template <int KIND> DI void attn_unit(const Params& P, int b, int h, int qb, char* shm, float lam, bool dry = false) {
;     ...
;     f32x16 pa0, pa1, pb0, pb1;
;     bf16x8 kf[4], x0, x1;
;     ATT_KLD(0, 0); ATT_XLD(0);
;     pa0 = MF(kf[0], qr[0], negm); pa1 = MF(kf[1], qr[0], negm); pa0 = MF(kf[2], qr[1], pa0); pa1 = MF(kf[3], qr[1], pa1);
;     SBAR(); ATT_KLD(0, 1); SBAR();
;     pa0 = MF(kf[0], qr[2], pa0); pa1 = MF(kf[1], qr[2], pa1); pa0 = MF(kf[2], qr[3], pa0); pa1 = MF(kf[3], qr[3], pa1);
;     if (KIND == 2) { pa0 = MF(x0, ones, pa0); pa1 = MF(x1, ones, pa1); }
;     ATT_FIX(pa0, pa1, ATT_TILE(0));
;     { float rm = max3f(pa0[0], pa0[1], pa1[0]), rm2 = max3f(pa0[2], pa0[3], pa1[1]); rm = max3f(rm, pa1[2], pa1[3]);
; #pragma unroll
;       for (int r = 4; r < 16; r += 4) { rm = max3f(rm, pa0[r], pa0[r + 1]); rm2 = max3f(rm2, pa0[r + 2], pa0[r + 3]); rm = max3f(rm, pa1[r], pa1[r + 1]); rm2 = max3f(rm2, pa1[r + 2], pa1[r + 3]); }
;       rm = swapmax(max3f(rm, rm2, rm2)); ATT_DECIDE(pa0, pa1, rm); }
;     for (int i = 0; i < nt_eff; ++i) {
;         ATT_STEP_BAR(i);
;         const int sn = (sc == 3 * SLOT) ? 0 : sc + SLOT;
;         const lds_cptr vp = shm3 + sc + 16384 + vlane;
;         bf16x8 vq[4]; bf16x8 pw[4]; u32x4 w0, w1; float sacc = 0.f;
;     ...
;         ATT_KLD(sn, 0); ATT_XLD(sn);
;         SBAR();
;     ...
;         G1(pb0 = MF(kf[0], qr[0], negm), 0, w0, 0);  G1(pb1 = MF(kf[1], qr[0], negm), 2, w0, 1);
;         G1(pb0 = MF(kf[2], qr[1], pb0), 4, w0, 2);   G1(pb1 = MF(kf[3], qr[1], pb1), 6, w0, 3);
;         ATT_KLD(sn, 1);
;         SBAR();
;         G1(pb0 = MF(kf[0], qr[2], pb0), 8, w1, 0);   G1(pb1 = MF(kf[1], qr[2], pb1), 10, w1, 1);
;         LDV(0); SBAR();
;         G1(pb0 = MF(kf[2], qr[3], pb0), 12, w1, 2);
;         LDV(1); SBAR();
;         G1(pb1 = MF(kf[3], qr[3], pb1), 14, w1, 3);
;         LDV(2); SBAR();
;     ...
;         if (KIND == 2) { pb0 = MF(x0, ones, pb0); pb1 = MF(x1, ones, pb1); }
;         pw[0] = __builtin_bit_cast(bf16x8, w0); pw[1] = __builtin_bit_cast(bf16x8, w1);
;     ...
;         if (NDB == 4) {
;             LDV(3); PVM(0); E4(0, w0, 0); PIN(pa1); PIN(sacc); PIN(w0); SBAR();
;             LDV(4); PVM(1); E4(2, w0, 1); PIN(pa1); PIN(sacc); PIN(w0); SBAR();
;             LDV(5); PVM(2); E4(4, w0, 2); PIN(pa1); PIN(sacc); PIN(w0); SBAR();
;             LDV(6); PVM(3); E4(6, w0, 3); PIN(pa1); PIN(sacc); PIN(w0); SBAR();
.LBB0_401:
	s_add_i32 s1, s3, 3
	s_cmp_lt_u32 s1, s18
	s_cselect_b32 s1, 1, 0
.LBB0_403:
	s_add_i32 s0, s5, 0x8400
	s_cmp_lg_u32 s5, 0x18c00
	s_cselect_b32 s0, s0, 0
	v_add_u32_e32 v168, s0, v193
	ds_read_b128 v[132:135], v168
	ds_read_b128 v[172:175], v168 offset:512
	ds_read_b128 v[176:179], v168 offset:2048
	ds_read_b128 v[180:183], v168 offset:2560
	v_add_u32_e32 v190, s5, v196
	s_waitcnt lgkmcnt(3)
	v_mfma_f32_32x32x16_bf16 v[116:131], v[132:135], v[160:163], v[4:19]
	v_exp_f32_e32 v100, v100
	v_exp_f32_e32 v101, v101
	v_add_f32_e32 v132, 0, v100
	v_add_f32_e32 v191, v101, v132
	v_cvt_pk_bf16_f32 v164, v100, v101
	s_waitcnt lgkmcnt(2)
	v_mfma_f32_32x32x16_bf16 v[132:147], v[172:175], v[160:163], v[4:19]
	s_cmp_eq_u32 s1, 0
	s_cbranch_scc1 .Lat1_nd0
	s_add_i32 m0, s11, s14
	s_nop 0
	global_load_lds_dwordx4 v[184:185], off
.Lat1_nd0:
	v_exp_f32_e32 v102, v102
	v_exp_f32_e32 v103, v103
	v_add_f32_e32 v165, v191, v102
	v_add_f32_e32 v172, v103, v165
	v_cvt_pk_bf16_f32 v165, v102, v103
	s_waitcnt lgkmcnt(1)
	v_mfma_f32_32x32x16_bf16 v[116:131], v[176:179], v[156:159], v[116:131]
	v_exp_f32_e32 v104, v104
	v_exp_f32_e32 v105, v105
	v_add_f32_e32 v166, v172, v104
	v_add_f32_e32 v172, v105, v166
	v_cvt_pk_bf16_f32 v166, v104, v105
	s_waitcnt lgkmcnt(0)
	v_mfma_f32_32x32x16_bf16 v[132:147], v[180:183], v[156:159], v[132:147]
	v_exp_f32_e32 v106, v106
	v_exp_f32_e32 v107, v107
	v_add_f32_e32 v167, v172, v106
	v_add_f32_e32 v191, v107, v167
	v_cvt_pk_bf16_f32 v167, v106, v107
	ds_read_b128 v[172:175], v168 offset:4096
	ds_read_b128 v[176:179], v168 offset:4608
	ds_read_b128 v[180:183], v168 offset:6144
	ds_read_b128 v[214:217], v168 offset:6656
	s_waitcnt lgkmcnt(3)
	v_mfma_f32_32x32x16_bf16 v[116:131], v[172:175], v[152:155], v[116:131]
	v_exp_f32_e32 v108, v108
	v_exp_f32_e32 v109, v109
	v_add_f32_e32 v168, v191, v108
	v_add_f32_e32 v172, v109, v168
	v_cvt_pk_bf16_f32 v168, v108, v109
	s_waitcnt lgkmcnt(2)
	v_mfma_f32_32x32x16_bf16 v[132:147], v[176:179], v[152:155], v[132:147]
	v_exp_f32_e32 v110, v110
	v_exp_f32_e32 v111, v111
	v_add_f32_e32 v169, v172, v110
	v_add_f32_e32 v176, v111, v169
	v_cvt_pk_bf16_f32 v169, v110, v111
	ds_read_b64_tr_b16 v[172:173], v190 offset:16384
	ds_read_b64_tr_b16 v[174:175], v190 offset:16896
	s_waitcnt lgkmcnt(3)
	v_mfma_f32_32x32x16_bf16 v[116:131], v[180:183], v[148:151], v[116:131]
	v_exp_f32_e32 v112, v112
	v_exp_f32_e32 v113, v113
	v_add_f32_e32 v170, v176, v112
	v_add_f32_e32 v180, v113, v170
	v_cvt_pk_bf16_f32 v170, v112, v113
	ds_read_b64_tr_b16 v[176:177], v190 offset:20480
	ds_read_b64_tr_b16 v[178:179], v190 offset:20992
	s_waitcnt lgkmcnt(4)
	v_mfma_f32_32x32x16_bf16 v[132:147], v[214:217], v[148:151], v[132:147]
	v_exp_f32_e32 v114, v114
	v_exp_f32_e32 v115, v115
	v_add_f32_e32 v171, v180, v114
	v_add_f32_e32 v180, v115, v171
	v_cvt_pk_bf16_f32 v171, v114, v115
	ds_read_b64_tr_b16 v[100:101], v190 offset:24576
	ds_read_b64_tr_b16 v[102:103], v190 offset:25088
	s_waitcnt lgkmcnt(4)
	v_mfma_f32_32x32x16_bf16 v[68:83], v[172:175], v[164:167], v[68:83]
	v_exp_f32_e32 v84, v84
	v_exp_f32_e32 v85, v85
	ds_read_b64_tr_b16 v[104:105], v190 offset:28672
	ds_read_b64_tr_b16 v[106:107], v190 offset:29184
	v_add_f32_e32 v108, v84, v180
	v_add_f32_e32 v180, v85, v108
	v_cvt_pk_bf16_f32 v108, v84, v85
	s_waitcnt lgkmcnt(4)
	v_mfma_f32_32x32x16_bf16 v[52:67], v[176:179], v[164:167], v[52:67]
	s_cmp_eq_u32 s1, 0
	s_cbranch_scc1 .Lat1_nd1
	s_add_i32 m0, s15, s14
	v_lshl_add_u64 v[214:215], v[184:185], 0, s[94:95]
	global_load_lds_dwordx4 v[214:215], off
.Lat1_nd1:
	v_exp_f32_e32 v86, v86
	ds_read_b64_tr_b16 v[112:113], v190 offset:17408
	ds_read_b64_tr_b16 v[114:115], v190 offset:17920
	v_exp_f32_e32 v87, v87
	v_add_f32_e32 v109, v180, v86
	v_add_f32_e32 v172, v87, v109
	v_cvt_pk_bf16_f32 v109, v86, v87
	s_waitcnt lgkmcnt(4)
	v_mfma_f32_32x32x16_bf16 v[36:51], v[100:103], v[164:167], v[36:51]
	v_exp_f32_e32 v88, v88
	ds_read_b64_tr_b16 v[176:177], v190 offset:21504
	ds_read_b64_tr_b16 v[178:179], v190 offset:22016
	v_exp_f32_e32 v89, v89
	v_add_f32_e32 v100, v172, v88
	v_add_f32_e32 v172, v89, v100
	v_cvt_pk_bf16_f32 v110, v88, v89
	s_waitcnt lgkmcnt(4)
	v_mfma_f32_32x32x16_bf16 v[20:35], v[104:107], v[164:167], v[20:35]
	v_exp_f32_e32 v90, v90
	v_exp_f32_e32 v91, v91
	ds_read_b64_tr_b16 v[100:101], v190 offset:25600
	ds_read_b64_tr_b16 v[102:103], v190 offset:26112
	v_add_f32_e32 v104, v172, v90
	v_cvt_pk_bf16_f32 v111, v90, v91
	v_add_f32_e32 v172, v91, v104
	s_waitcnt lgkmcnt(4)
	v_mfma_f32_32x32x16_bf16 v[68:83], v[112:115], v[168:171], v[68:83]
	v_exp_f32_e32 v92, v92
	v_exp_f32_e32 v93, v93
	ds_read_b64_tr_b16 v[104:105], v190 offset:29696
	ds_read_b64_tr_b16 v[106:107], v190 offset:30208
	v_add_f32_e32 v164, v172, v92
	v_add_f32_e32 v180, v93, v164
	v_cvt_pk_bf16_f32 v112, v92, v93
	s_waitcnt lgkmcnt(4)
	v_mfma_f32_32x32x16_bf16 v[52:67], v[176:179], v[168:171], v[52:67]
	v_exp_f32_e32 v94, v94
	ds_read_b64_tr_b16 v[172:173], v190 offset:18432
	ds_read_b64_tr_b16 v[174:175], v190 offset:18944
	v_exp_f32_e32 v95, v95
	v_add_f32_e32 v165, v180, v94
	v_add_f32_e32 v166, v95, v165
	v_cvt_pk_bf16_f32 v113, v94, v95
	s_waitcnt lgkmcnt(4)
	v_mfma_f32_32x32x16_bf16 v[36:51], v[100:103], v[168:171], v[36:51]
	v_exp_f32_e32 v96, v96
	ds_read_b64_tr_b16 v[176:177], v190 offset:22528
	ds_read_b64_tr_b16 v[178:179], v190 offset:23040
	v_exp_f32_e32 v97, v97
	v_add_f32_e32 v100, v166, v96
	v_add_f32_e32 v100, v97, v100
	v_cvt_pk_bf16_f32 v114, v96, v97
	s_waitcnt lgkmcnt(4)
	v_mfma_f32_32x32x16_bf16 v[20:35], v[104:107], v[168:171], v[20:35]
	v_exp_f32_e32 v98, v98
	v_exp_f32_e32 v99, v99
	ds_read_b64_tr_b16 v[180:181], v190 offset:26624
	ds_read_b64_tr_b16 v[182:183], v190 offset:27136
	v_add_f32_e32 v100, v100, v98
	v_cvt_pk_bf16_f32 v115, v98, v99
	v_add_f32_e32 v100, v99, v100
	s_cmp_le_i32 s4, s13
	s_cbranch_scc1 .LBB0_405
; DI float max3f(float a, float b, float c) { float r; asm("v_max3_f32 %0, %1, %2, %3" : "=v"(r) : "v"(a), "v"(b), "v"(c)); return r; }
; #define SBAR() __builtin_amdgcn_sched_barrier(0)
; #define PIN(x) asm volatile("" : "+v"(x))
; #define LDV(j_) do { if ((j_) < 4 * NDB) { const lds_cptr a_ = vp + ((j_) % NDB) * 4096 + ((j_) / NDB) * 1024; const s16x4 lo_ = vtr(a_), hi_ = vtr(a_ + 512); \
;             vq[(j_) & 3] = (bf16x8){lo_[0], lo_[1], lo_[2], lo_[3], hi_[0], hi_[1], hi_[2], hi_[3]}; } } while (0)
; #define PVM(j_) o[(j_) % NDB] = MF(vq[(j_) & 3], pw[(j_) / NDB], o[(j_) % NDB])
; template <int KIND> DI void attn_unit(const Params& P, int b, int h, int qb, char* shm, float lam, bool dry = false) {
;     ...
;         ATT_FIX(pb0, pb1, ATT_TILE(i + 1));
;         float rm, rm2;
;         if (NDB == 4) {
;             LDV(11); PVM(8); rm = max3f(pb0[0], pb0[1], pb1[0]); rm2 = max3f(pb0[2], pb0[3], pb1[1]); PIN(rm); PIN(rm2); SBAR();
;             LDV(12); PVM(9); rm = max3f(rm, pb1[2], pb1[3]); rm2 = max3f(rm2, pb0[4], pb0[5]); PIN(rm); PIN(rm2); SBAR();
;             LDV(13); PVM(10); rm = max3f(rm, pb0[6], pb0[7]); rm2 = max3f(rm2, pb1[4], pb1[5]); PIN(rm); PIN(rm2); SBAR();
;             LDV(14); PVM(11); rm = max3f(rm, pb1[6], pb1[7]); rm2 = max3f(rm2, pb0[8], pb0[9]); PIN(rm); PIN(rm2); SBAR();
;             LDV(15); PVM(12); rm = max3f(rm, pb0[10], pb0[11]); rm2 = max3f(rm2, pb1[8], pb1[9]); PIN(rm); PIN(rm2); SBAR();
;             PVM(13); rm = max3f(rm, pb1[10], pb1[11]); rm2 = max3f(rm2, pb0[12], pb0[13]); PIN(rm); PIN(rm2); SBAR();
;             PVM(14); rm = max3f(rm, pb0[14], pb0[15]); rm2 = max3f(rm2, pb1[12], pb1[13]); PIN(rm); PIN(rm2); SBAR();
;             PVM(15); rm = max3f(rm, pb1[14], pb1[15]); PIN(rm); SBAR();
	ds_read2_b32 v[84:85], v192 offset1:1
	ds_read2_b32 v[86:87], v192 offset0:2 offset1:3
	ds_read2_b32 v[88:89], v192 offset0:8 offset1:9
	ds_read2_b32 v[90:91], v192 offset0:10 offset1:11
	ds_read2_b32 v[92:93], v192 offset0:16 offset1:17
	ds_read2_b32 v[94:95], v192 offset0:18 offset1:19
	ds_read2_b32 v[96:97], v192 offset0:24 offset1:25
	ds_read2_b32 v[98:99], v192 offset0:26 offset1:27
	ds_read2_b32 v[102:103], v192 offset0:32 offset1:33
	ds_read2_b32 v[104:105], v192 offset0:34 offset1:35
	ds_read2_b32 v[106:107], v192 offset0:40 offset1:41
	ds_read2_b32 v[164:165], v192 offset0:42 offset1:43
	s_waitcnt lgkmcnt(11)
	v_pk_add_f32 v[116:117], v[116:117], v[84:85]
	s_waitcnt lgkmcnt(5)
	v_pk_add_f32 v[128:129], v[128:129], v[96:97]
	v_pk_add_f32 v[126:127], v[126:127], v[94:95]
	v_pk_add_f32 v[124:125], v[124:125], v[92:93]
	ds_read2_b32 v[84:85], v192 offset0:48 offset1:49
	ds_read2_b32 v[92:93], v192 offset0:50 offset1:51
	ds_read2_b32 v[94:95], v192 offset0:56 offset1:57
	ds_read2_b32 v[96:97], v192 offset0:58 offset1:59
	s_waitcnt lgkmcnt(8)
	v_pk_add_f32 v[130:131], v[130:131], v[98:99]
	v_pk_add_f32 v[122:123], v[122:123], v[90:91]
	v_pk_add_f32 v[120:121], v[120:121], v[88:89]
	v_pk_add_f32 v[118:119], v[118:119], v[86:87]
	s_waitcnt lgkmcnt(7)
	v_pk_add_f32 v[132:133], v[132:133], v[102:103]
	s_waitcnt lgkmcnt(0)
	v_pk_add_f32 v[146:147], v[146:147], v[96:97]
	v_pk_add_f32 v[144:145], v[144:145], v[94:95]
	v_pk_add_f32 v[142:143], v[142:143], v[92:93]
	v_pk_add_f32 v[140:141], v[140:141], v[84:85]
	v_pk_add_f32 v[138:139], v[138:139], v[164:165]
	v_pk_add_f32 v[136:137], v[136:137], v[106:107]
	v_pk_add_f32 v[134:135], v[134:135], v[104:105]
.LBB0_405:
	s_waitcnt lgkmcnt(4)
	v_mfma_f32_32x32x16_bf16 v[68:83], v[172:175], v[108:111], v[68:83]
	s_cmp_eq_u32 s1, 0
	s_cbranch_scc1 .Lat1_nd2
	s_add_i32 m0, s16, s14
	s_nop 0
	global_load_lds_dwordx4 v[186:187], off
.Lat1_nd2:
	s_cmp_lt_u32 s3, s7
	s_cbranch_scc1 .Lat1_nomask
	v_mov_b32_e32 v116, v245
	v_mov_b32_e32 v117, v245
	v_mov_b32_e32 v118, v245
	v_mov_b32_e32 v119, v245
	v_mov_b32_e32 v120, v245
	v_mov_b32_e32 v121, v245
	v_mov_b32_e32 v122, v245
	v_mov_b32_e32 v123, v245
	v_mov_b32_e32 v124, v245
	v_mov_b32_e32 v125, v245
	v_mov_b32_e32 v126, v245
	v_mov_b32_e32 v127, v245
	v_mov_b32_e32 v128, v245
	v_mov_b32_e32 v129, v245
	v_mov_b32_e32 v130, v245
	v_mov_b32_e32 v131, v245
	v_mov_b32_e32 v132, v245
	v_mov_b32_e32 v133, v245
	v_mov_b32_e32 v134, v245
	v_mov_b32_e32 v135, v245
	v_mov_b32_e32 v136, v245
	v_mov_b32_e32 v137, v245
	v_mov_b32_e32 v138, v245
	v_mov_b32_e32 v139, v245
	v_mov_b32_e32 v140, v245
	v_mov_b32_e32 v141, v245
	v_mov_b32_e32 v142, v245
	v_mov_b32_e32 v143, v245
	v_mov_b32_e32 v144, v245
	v_mov_b32_e32 v145, v245
	v_mov_b32_e32 v146, v245
	v_mov_b32_e32 v147, v245
.Lat1_nomask:
	v_add_f32_e32 v197, v197, v100
	ds_read_b64_tr_b16 v[84:85], v190 offset:30720
	ds_read_b64_tr_b16 v[86:87], v190 offset:31232
	v_max3_f32 v100, v116, v117, v132
	v_max3_f32 v101, v118, v119, v133
	s_waitcnt lgkmcnt(4)
	v_mfma_f32_32x32x16_bf16 v[52:67], v[176:179], v[108:111], v[52:67]
	ds_read_b64_tr_b16 v[88:89], v190 offset:19456
	ds_read_b64_tr_b16 v[90:91], v190 offset:19968
	v_max3_f32 v100, v100, v134, v135
	v_max3_f32 v101, v101, v120, v121
	s_waitcnt lgkmcnt(4)
	v_mfma_f32_32x32x16_bf16 v[36:51], v[180:183], v[108:111], v[36:51]
	ds_read_b64_tr_b16 v[92:93], v190 offset:23552
	ds_read_b64_tr_b16 v[94:95], v190 offset:24064
	v_max3_f32 v100, v100, v122, v123
	v_max3_f32 v101, v101, v136, v137
	s_waitcnt lgkmcnt(4)
	v_mfma_f32_32x32x16_bf16 v[20:35], v[84:87], v[108:111], v[20:35]
	ds_read_b64_tr_b16 v[96:97], v190 offset:27648
	ds_read_b64_tr_b16 v[98:99], v190 offset:28160
	v_max3_f32 v100, v100, v138, v139
	v_max3_f32 v101, v101, v124, v125
	s_waitcnt lgkmcnt(4)
	v_mfma_f32_32x32x16_bf16 v[68:83], v[88:91], v[112:115], v[68:83]
	s_cmp_eq_u32 s1, 0
	s_cbranch_scc1 .Lat1_nd3
	s_add_i32 m0, s17, s14
	v_lshl_add_u64 v[214:215], v[186:187], 0, s[94:95]
	global_load_lds_dwordx4 v[214:215], off
; #define LAS __attribute__((address_space(3)))
; DI float max3f(float a, float b, float c) { float r; asm("v_max3_f32 %0, %1, %2, %3" : "=v"(r) : "v"(a), "v"(b), "v"(c)); return r; }
; DI float swapmax(float m) { auto rr = __builtin_amdgcn_permlane32_swap(__float_as_uint(m), __float_as_uint(m), false, false); return fmaxf(__uint_as_float(rr[0]), __uint_as_float(rr[1])); }
; DI float swapsum(float m) { auto rr = __builtin_amdgcn_permlane32_swap(__float_as_uint(m), __float_as_uint(m), false, false); return __uint_as_float(rr[0]) + __uint_as_float(rr[1]); }
; template <int KIND> DI void attn_unit(const Params& P, int b, int h, int qb, char* shm, float lam, bool dry = false) {
;     ...
;             PVM(13); rm = max3f(rm, pb1[10], pb1[11]); rm2 = max3f(rm2, pb0[12], pb0[13]); PIN(rm); PIN(rm2); SBAR();
;             PVM(14); rm = max3f(rm, pb0[14], pb0[15]); rm2 = max3f(rm2, pb1[12], pb1[13]); PIN(rm); PIN(rm2); SBAR();
;             PVM(15); rm = max3f(rm, pb1[14], pb1[15]); PIN(rm); SBAR();
;         } else {
;             LDV(7); PVM(4); rm = max3f(pb0[0], pb0[1], pb1[0]); rm2 = max3f(pb0[2], pb0[3], pb1[1]); rm = max3f(rm, pb1[2], pb1[3]); rm2 = max3f(rm2, pb0[4], pb0[5]); PIN(rm); PIN(rm2); SBAR();
;             PVM(5); rm = max3f(rm, pb0[6], pb0[7]); rm2 = max3f(rm2, pb1[4], pb1[5]); rm = max3f(rm, pb1[6], pb1[7]); rm2 = max3f(rm2, pb0[8], pb0[9]); PIN(rm); PIN(rm2); SBAR();
;             PVM(6); rm = max3f(rm, pb0[10], pb0[11]); rm2 = max3f(rm2, pb1[8], pb1[9]); rm = max3f(rm, pb1[10], pb1[11]); rm2 = max3f(rm2, pb0[12], pb0[13]); PIN(rm); PIN(rm2); SBAR();
;             PVM(7); rm = max3f(rm, pb0[14], pb0[15]); rm2 = max3f(rm2, pb1[12], pb1[13]); rm = max3f(rm, pb1[14], pb1[15]); PIN(rm); PIN(rm2); SBAR();
;         }
;     ...
;         rm = swapmax(max3f(rm, rm2, rm2));
;         if (KIND == 2) {
;             const u32x2 kx = *(const LAS u32x2*)(shm3 + sc + 32768);
;             const float xk0 = __uint_as_float(kx.x << 16) + __uint_as_float(kx.x & 0xffff0000u) + __uint_as_float(kx.y << 16);
;             const float ltot = swapsum(lsum);
;             const bool ok = (qkmax + cb + xk0) < (mhat + __builtin_amdgcn_logf(ltot) - 54.0f);
;             const bool allok = __all(ok) && !(ATT_TILE(i) > wt_hi);
;             if (lane == 0) vote[8 * (i & 3) + wid] = allok ? 1u : 0u;
;         }
;         if (i + 1 < nt_eff) ATT_DECIDE(pb0, pb1, rm);
.Lat1_nd3:
	ds_read_b64_tr_b16 v[84:85], v190 offset:31744
	ds_read_b64_tr_b16 v[86:87], v190 offset:32256
	v_max3_f32 v100, v100, v126, v127
	v_max3_f32 v101, v101, v140, v141
	s_waitcnt lgkmcnt(4)
	v_mfma_f32_32x32x16_bf16 v[52:67], v[92:95], v[112:115], v[52:67]
	v_max3_f32 v100, v100, v142, v143
	v_max3_f32 v101, v101, v128, v129
	s_waitcnt lgkmcnt(2)
	v_mfma_f32_32x32x16_bf16 v[36:51], v[96:99], v[112:115], v[36:51]
	v_max3_f32 v100, v100, v130, v131
	v_max3_f32 v101, v101, v144, v145
	s_waitcnt lgkmcnt(0)
	v_mfma_f32_32x32x16_bf16 v[20:35], v[84:87], v[112:115], v[20:35]
	v_max3_f32 v100, v100, v146, v147
	v_max3_f32 v100, v100, v101, v101
	s_add_i32 s3, s3, 1
	v_mov_b32_e32 v101, v100
	s_cmp_ge_u32 s3, s18
	s_nop 0
	v_permlane32_swap_b32_e32 v100, v101
	s_cbranch_scc1 .LBB0_408
	v_max_f32_e32 v100, v100, v100
	v_max_f32_e32 v101, v101, v101
	v_max_f32_e32 v100, v100, v101
	v_cmp_lt_f32_e32 vcc, s88, v100
	s_cbranch_vccz .LBB0_408
	v_max_f32_e32 v100, v100, v100
	v_max_f32_e32 v101, 0, v100
	v_exp_f32_e64 v100, -v101
	v_sub_f32_e32 v131, v131, v101
	v_sub_f32_e32 v130, v130, v101
	v_sub_f32_e32 v129, v129, v101
	v_pk_mul_f32 v[82:83], v[82:83], v[100:101] op_sel_hi:[1,0]
	v_pk_mul_f32 v[80:81], v[80:81], v[100:101] op_sel_hi:[1,0]
	v_pk_mul_f32 v[78:79], v[78:79], v[100:101] op_sel_hi:[1,0]
	v_pk_mul_f32 v[76:77], v[76:77], v[100:101] op_sel_hi:[1,0]
	v_pk_mul_f32 v[74:75], v[74:75], v[100:101] op_sel_hi:[1,0]
	v_pk_mul_f32 v[72:73], v[72:73], v[100:101] op_sel_hi:[1,0]
	v_pk_mul_f32 v[70:71], v[70:71], v[100:101] op_sel_hi:[1,0]
	v_pk_mul_f32 v[68:69], v[68:69], v[100:101] op_sel_hi:[1,0]
	v_pk_mul_f32 v[66:67], v[66:67], v[100:101] op_sel_hi:[1,0]
	v_pk_mul_f32 v[64:65], v[64:65], v[100:101] op_sel_hi:[1,0]
	v_pk_mul_f32 v[62:63], v[62:63], v[100:101] op_sel_hi:[1,0]
	v_pk_mul_f32 v[60:61], v[60:61], v[100:101] op_sel_hi:[1,0]
	v_pk_mul_f32 v[58:59], v[58:59], v[100:101] op_sel_hi:[1,0]
	v_pk_mul_f32 v[56:57], v[56:57], v[100:101] op_sel_hi:[1,0]
	v_pk_mul_f32 v[54:55], v[54:55], v[100:101] op_sel_hi:[1,0]
	v_pk_mul_f32 v[52:53], v[52:53], v[100:101] op_sel_hi:[1,0]
	v_pk_mul_f32 v[50:51], v[50:51], v[100:101] op_sel_hi:[1,0]
	v_pk_mul_f32 v[48:49], v[48:49], v[100:101] op_sel_hi:[1,0]
	v_pk_mul_f32 v[46:47], v[46:47], v[100:101] op_sel_hi:[1,0]
	v_pk_mul_f32 v[44:45], v[44:45], v[100:101] op_sel_hi:[1,0]
	v_pk_mul_f32 v[42:43], v[42:43], v[100:101] op_sel_hi:[1,0]
	v_pk_mul_f32 v[40:41], v[40:41], v[100:101] op_sel_hi:[1,0]
	v_pk_mul_f32 v[38:39], v[38:39], v[100:101] op_sel_hi:[1,0]
	v_pk_mul_f32 v[36:37], v[36:37], v[100:101] op_sel_hi:[1,0]
	v_pk_mul_f32 v[34:35], v[34:35], v[100:101] op_sel_hi:[1,0]
	v_pk_mul_f32 v[32:33], v[32:33], v[100:101] op_sel_hi:[1,0]
	v_pk_mul_f32 v[30:31], v[30:31], v[100:101] op_sel_hi:[1,0]
	v_pk_mul_f32 v[28:29], v[28:29], v[100:101] op_sel_hi:[1,0]
	v_pk_mul_f32 v[26:27], v[26:27], v[100:101] op_sel_hi:[1,0]
	v_pk_mul_f32 v[24:25], v[24:25], v[100:101] op_sel_hi:[1,0]
	v_pk_mul_f32 v[22:23], v[22:23], v[100:101] op_sel_hi:[1,0]
	v_pk_mul_f32 v[20:21], v[20:21], v[100:101] op_sel_hi:[1,0]
	v_sub_f32_e32 v128, v128, v101
	v_sub_f32_e32 v127, v127, v101
	v_sub_f32_e32 v126, v126, v101
	v_sub_f32_e32 v125, v125, v101
	v_sub_f32_e32 v124, v124, v101
	v_sub_f32_e32 v123, v123, v101
	v_sub_f32_e32 v122, v122, v101
	v_sub_f32_e32 v121, v121, v101
	v_sub_f32_e32 v120, v120, v101
	v_sub_f32_e32 v119, v119, v101
	v_sub_f32_e32 v118, v118, v101
	v_sub_f32_e32 v117, v117, v101
	v_sub_f32_e32 v116, v116, v101
	v_sub_f32_e32 v147, v147, v101
	v_sub_f32_e32 v146, v146, v101
	v_sub_f32_e32 v145, v145, v101
	v_sub_f32_e32 v144, v144, v101
	v_sub_f32_e32 v143, v143, v101
	v_sub_f32_e32 v142, v142, v101
	v_sub_f32_e32 v141, v141, v101
	v_sub_f32_e32 v140, v140, v101
	v_sub_f32_e32 v139, v139, v101
	v_sub_f32_e32 v138, v138, v101
	v_sub_f32_e32 v137, v137, v101
	v_sub_f32_e32 v136, v136, v101
	v_sub_f32_e32 v135, v135, v101
	v_sub_f32_e32 v134, v134, v101
	v_sub_f32_e32 v133, v133, v101
	v_sub_f32_e32 v132, v132, v101
	v_sub_f32_e32 v19, v19, v101
	v_sub_f32_e32 v18, v18, v101
	v_sub_f32_e32 v17, v17, v101
	v_sub_f32_e32 v16, v16, v101
	v_sub_f32_e32 v15, v15, v101
	v_sub_f32_e32 v14, v14, v101
	v_sub_f32_e32 v13, v13, v101
	v_sub_f32_e32 v12, v12, v101
	v_sub_f32_e32 v11, v11, v101
	v_sub_f32_e32 v10, v10, v101
	v_sub_f32_e32 v9, v9, v101
	v_sub_f32_e32 v8, v8, v101
	v_sub_f32_e32 v7, v7, v101
	v_sub_f32_e32 v6, v6, v101
	v_sub_f32_e32 v5, v5, v101
	v_sub_f32_e32 v4, v4, v101
	v_mul_f32_e32 v197, v197, v100

; template <int KIND> DI void attn_unit(const Params& P, int b, int h, int qb, char* shm, float lam, bool dry = false) {
;     ...
;     f32x16 pa0, pa1, pb0, pb1;
;     bf16x8 kf[4], x0, x1;
;     ATT_KLD(0, 0); ATT_XLD(0);
;     pa0 = MF(kf[0], qr[0], negm); pa1 = MF(kf[1], qr[0], negm); pa0 = MF(kf[2], qr[1], pa0); pa1 = MF(kf[3], qr[1], pa1);
;     SBAR(); ATT_KLD(0, 1); SBAR();
;     pa0 = MF(kf[0], qr[2], pa0); pa1 = MF(kf[1], qr[2], pa1); pa0 = MF(kf[2], qr[3], pa0); pa1 = MF(kf[3], qr[3], pa1);
;     if (KIND == 2) { pa0 = MF(x0, ones, pa0); pa1 = MF(x1, ones, pa1); }
;     ATT_FIX(pa0, pa1, ATT_TILE(0));
;     { float rm = max3f(pa0[0], pa0[1], pa1[0]), rm2 = max3f(pa0[2], pa0[3], pa1[1]); rm = max3f(rm, pa1[2], pa1[3]);
; #pragma unroll
;       for (int r = 4; r < 16; r += 4) { rm = max3f(rm, pa0[r], pa0[r + 1]); rm2 = max3f(rm2, pa0[r + 2], pa0[r + 3]); rm = max3f(rm, pa1[r], pa1[r + 1]); rm2 = max3f(rm2, pa1[r + 2], pa1[r + 3]); }
;       rm = swapmax(max3f(rm, rm2, rm2)); ATT_DECIDE(pa0, pa1, rm); }
;     for (int i = 0; i < nt_eff; ++i) {
;         ATT_STEP_BAR(i);
;         const int sn = (sc == 3 * SLOT) ? 0 : sc + SLOT;
;         const lds_cptr vp = shm3 + sc + 16384 + vlane;
;         bf16x8 vq[4]; bf16x8 pw[4]; u32x4 w0, w1; float sacc = 0.f;
;     ...
;         ATT_KLD(sn, 0); ATT_XLD(sn);
;         SBAR();
;     ...
;         G1(pb0 = MF(kf[0], qr[0], negm), 0, w0, 0);  G1(pb1 = MF(kf[1], qr[0], negm), 2, w0, 1);
;         G1(pb0 = MF(kf[2], qr[1], pb0), 4, w0, 2);   G1(pb1 = MF(kf[3], qr[1], pb1), 6, w0, 3);
;         ATT_KLD(sn, 1);
;         SBAR();
;         G1(pb0 = MF(kf[0], qr[2], pb0), 8, w1, 0);   G1(pb1 = MF(kf[1], qr[2], pb1), 10, w1, 1);
;         LDV(0); SBAR();
;         G1(pb0 = MF(kf[2], qr[3], pb0), 12, w1, 2);
;         LDV(1); SBAR();
;         G1(pb1 = MF(kf[3], qr[3], pb1), 14, w1, 3);
;         LDV(2); SBAR();
;     ...
;         if (KIND == 2) { pb0 = MF(x0, ones, pb0); pb1 = MF(x1, ones, pb1); }
;         pw[0] = __builtin_bit_cast(bf16x8, w0); pw[1] = __builtin_bit_cast(bf16x8, w1);
;     ...
;         if (NDB == 4) {
;             LDV(3); PVM(0); E4(0, w0, 0); PIN(pa1); PIN(sacc); PIN(w0); SBAR();
;             LDV(4); PVM(1); E4(2, w0, 1); PIN(pa1); PIN(sacc); PIN(w0); SBAR();
;             LDV(5); PVM(2); E4(4, w0, 2); PIN(pa1); PIN(sacc); PIN(w0); SBAR();
;             LDV(6); PVM(3); E4(6, w0, 3); PIN(pa1); PIN(sacc); PIN(w0); SBAR();
.Lat2_403:
	s_add_i32 s0, s5, 0x8400
	s_cmp_lg_u32 s5, 0x18c00
	s_cselect_b32 s0, s0, 0
	v_add_u32_e32 v168, s0, v193
	ds_read_b128 v[84:87], v168
	ds_read_b128 v[172:175], v168 offset:512
	ds_read_b128 v[176:179], v168 offset:2048
	ds_read_b128 v[180:183], v168 offset:2560
	v_add_u32_e32 v190, s5, v196
	s_waitcnt lgkmcnt(3)
	v_mfma_f32_32x32x16_bf16 v[100:115], v[84:87], v[160:163], v[4:19]
	v_exp_f32_e32 v116, v116
	v_exp_f32_e32 v117, v117
	v_add_f32_e32 v84, 0, v116
	v_add_f32_e32 v191, v117, v84
	v_cvt_pk_bf16_f32 v164, v116, v117
	s_waitcnt lgkmcnt(2)
	v_mfma_f32_32x32x16_bf16 v[84:99], v[172:175], v[160:163], v[4:19]
	s_cmp_eq_u32 s1, 0
	s_cbranch_scc1 .Lat2_nd0
	s_add_i32 m0, s11, s14
	s_nop 0
	global_load_lds_dwordx4 v[184:185], off
.Lat2_nd0:
	v_exp_f32_e32 v118, v118
	v_exp_f32_e32 v119, v119
	v_add_f32_e32 v165, v191, v118
	v_add_f32_e32 v172, v119, v165
	v_cvt_pk_bf16_f32 v165, v118, v119
	s_waitcnt lgkmcnt(1)
	v_mfma_f32_32x32x16_bf16 v[100:115], v[176:179], v[156:159], v[100:115]
	v_exp_f32_e32 v120, v120
	v_exp_f32_e32 v121, v121
	v_add_f32_e32 v166, v172, v120
	v_add_f32_e32 v172, v121, v166
	v_cvt_pk_bf16_f32 v166, v120, v121
	s_waitcnt lgkmcnt(0)
	v_mfma_f32_32x32x16_bf16 v[84:99], v[180:183], v[156:159], v[84:99]
	v_exp_f32_e32 v122, v122
	v_exp_f32_e32 v123, v123
	v_add_f32_e32 v167, v172, v122
	v_add_f32_e32 v191, v123, v167
	v_cvt_pk_bf16_f32 v167, v122, v123
	ds_read_b128 v[172:175], v168 offset:4096
	ds_read_b128 v[176:179], v168 offset:4608
	ds_read_b128 v[180:183], v168 offset:6144
	ds_read_b128 v[214:217], v168 offset:6656
	s_waitcnt lgkmcnt(3)
	v_mfma_f32_32x32x16_bf16 v[100:115], v[172:175], v[152:155], v[100:115]
	v_exp_f32_e32 v124, v124
	v_exp_f32_e32 v125, v125
	v_add_f32_e32 v168, v191, v124
	v_add_f32_e32 v172, v125, v168
	v_cvt_pk_bf16_f32 v168, v124, v125
	s_waitcnt lgkmcnt(2)
	v_mfma_f32_32x32x16_bf16 v[84:99], v[176:179], v[152:155], v[84:99]
	v_exp_f32_e32 v126, v126
	v_exp_f32_e32 v127, v127
	v_add_f32_e32 v169, v172, v126
	v_add_f32_e32 v176, v127, v169
	v_cvt_pk_bf16_f32 v169, v126, v127
	ds_read_b64_tr_b16 v[172:173], v190 offset:16384
	ds_read_b64_tr_b16 v[174:175], v190 offset:16896
	s_waitcnt lgkmcnt(3)
	v_mfma_f32_32x32x16_bf16 v[100:115], v[180:183], v[148:151], v[100:115]
	v_exp_f32_e32 v128, v128
	v_exp_f32_e32 v129, v129
	v_add_f32_e32 v170, v176, v128
	v_add_f32_e32 v180, v129, v170
	v_cvt_pk_bf16_f32 v170, v128, v129
	ds_read_b64_tr_b16 v[176:177], v190 offset:20480
	ds_read_b64_tr_b16 v[178:179], v190 offset:20992
	s_waitcnt lgkmcnt(4)
	v_mfma_f32_32x32x16_bf16 v[84:99], v[214:217], v[148:151], v[84:99]
	v_exp_f32_e32 v130, v130
	v_exp_f32_e32 v131, v131
	v_add_f32_e32 v171, v180, v130
	v_add_f32_e32 v180, v131, v171
	v_cvt_pk_bf16_f32 v171, v130, v131
	ds_read_b64_tr_b16 v[116:117], v190 offset:24576
	ds_read_b64_tr_b16 v[118:119], v190 offset:25088
	s_waitcnt lgkmcnt(4)
	v_mfma_f32_32x32x16_bf16 v[68:83], v[172:175], v[164:167], v[68:83]
	v_exp_f32_e32 v132, v132
	v_exp_f32_e32 v133, v133
	ds_read_b64_tr_b16 v[120:121], v190 offset:28672
	ds_read_b64_tr_b16 v[122:123], v190 offset:29184
	v_add_f32_e32 v124, v132, v180
	v_add_f32_e32 v180, v133, v124
	v_cvt_pk_bf16_f32 v124, v132, v133
	s_waitcnt lgkmcnt(4)
	v_mfma_f32_32x32x16_bf16 v[52:67], v[176:179], v[164:167], v[52:67]
	s_cmp_eq_u32 s1, 0
	s_cbranch_scc1 .Lat2_nd1
	s_add_i32 m0, s15, s14
	v_lshl_add_u64 v[214:215], v[184:185], 0, s[94:95]
	global_load_lds_dwordx4 v[214:215], off
.Lat2_nd1:
	v_exp_f32_e32 v134, v134
	ds_read_b64_tr_b16 v[128:129], v190 offset:17408
	ds_read_b64_tr_b16 v[130:131], v190 offset:17920
	v_exp_f32_e32 v135, v135
	v_add_f32_e32 v125, v180, v134
	v_add_f32_e32 v172, v135, v125
	v_cvt_pk_bf16_f32 v125, v134, v135
	s_waitcnt lgkmcnt(4)
	v_mfma_f32_32x32x16_bf16 v[36:51], v[116:119], v[164:167], v[36:51]
	v_exp_f32_e32 v136, v136
	ds_read_b64_tr_b16 v[176:177], v190 offset:21504
	ds_read_b64_tr_b16 v[178:179], v190 offset:22016
	v_exp_f32_e32 v137, v137
	v_add_f32_e32 v116, v172, v136
	v_add_f32_e32 v172, v137, v116
	v_cvt_pk_bf16_f32 v126, v136, v137
	s_waitcnt lgkmcnt(4)
	v_mfma_f32_32x32x16_bf16 v[20:35], v[120:123], v[164:167], v[20:35]
	v_exp_f32_e32 v138, v138
	v_exp_f32_e32 v139, v139
	ds_read_b64_tr_b16 v[116:117], v190 offset:25600
	ds_read_b64_tr_b16 v[118:119], v190 offset:26112
	v_add_f32_e32 v120, v172, v138
	v_cvt_pk_bf16_f32 v127, v138, v139
	v_add_f32_e32 v172, v139, v120
	s_waitcnt lgkmcnt(4)
	v_mfma_f32_32x32x16_bf16 v[68:83], v[128:131], v[168:171], v[68:83]
	v_exp_f32_e32 v140, v140
	v_exp_f32_e32 v141, v141
	ds_read_b64_tr_b16 v[120:121], v190 offset:29696
	ds_read_b64_tr_b16 v[122:123], v190 offset:30208
	v_add_f32_e32 v164, v172, v140
	v_add_f32_e32 v180, v141, v164
	v_cvt_pk_bf16_f32 v128, v140, v141
	s_waitcnt lgkmcnt(4)
	v_mfma_f32_32x32x16_bf16 v[52:67], v[176:179], v[168:171], v[52:67]
	v_exp_f32_e32 v142, v142
	ds_read_b64_tr_b16 v[172:173], v190 offset:18432
	ds_read_b64_tr_b16 v[174:175], v190 offset:18944
	v_exp_f32_e32 v143, v143
	v_add_f32_e32 v165, v180, v142
	v_add_f32_e32 v166, v143, v165
	v_cvt_pk_bf16_f32 v129, v142, v143
	s_waitcnt lgkmcnt(4)
	v_mfma_f32_32x32x16_bf16 v[36:51], v[116:119], v[168:171], v[36:51]
	v_exp_f32_e32 v144, v144
	ds_read_b64_tr_b16 v[176:177], v190 offset:22528
	ds_read_b64_tr_b16 v[178:179], v190 offset:23040
	v_exp_f32_e32 v145, v145
	v_add_f32_e32 v116, v166, v144
	v_add_f32_e32 v116, v145, v116
	v_cvt_pk_bf16_f32 v130, v144, v145
	s_waitcnt lgkmcnt(4)
	v_mfma_f32_32x32x16_bf16 v[20:35], v[120:123], v[168:171], v[20:35]
	v_exp_f32_e32 v146, v146
	v_exp_f32_e32 v147, v147
	ds_read_b64_tr_b16 v[180:181], v190 offset:26624
	ds_read_b64_tr_b16 v[182:183], v190 offset:27136
	v_add_f32_e32 v116, v116, v146
	v_cvt_pk_bf16_f32 v131, v146, v147
	v_add_f32_e32 v116, v147, v116
	s_cmp_le_i32 s4, s13
	s_cbranch_scc1 .Lat2_405
; DI float max3f(float a, float b, float c) { float r; asm("v_max3_f32 %0, %1, %2, %3" : "=v"(r) : "v"(a), "v"(b), "v"(c)); return r; }
; #define SBAR() __builtin_amdgcn_sched_barrier(0)
; #define PIN(x) asm volatile("" : "+v"(x))
; #define LDV(j_) do { if ((j_) < 4 * NDB) { const lds_cptr a_ = vp + ((j_) % NDB) * 4096 + ((j_) / NDB) * 1024; const s16x4 lo_ = vtr(a_), hi_ = vtr(a_ + 512); \
;             vq[(j_) & 3] = (bf16x8){lo_[0], lo_[1], lo_[2], lo_[3], hi_[0], hi_[1], hi_[2], hi_[3]}; } } while (0)
; #define PVM(j_) o[(j_) % NDB] = MF(vq[(j_) & 3], pw[(j_) / NDB], o[(j_) % NDB])
; template <int KIND> DI void attn_unit(const Params& P, int b, int h, int qb, char* shm, float lam, bool dry = false) {
;     ...
;         ATT_FIX(pb0, pb1, ATT_TILE(i + 1));
;         float rm, rm2;
;         if (NDB == 4) {
;             LDV(11); PVM(8); rm = max3f(pb0[0], pb0[1], pb1[0]); rm2 = max3f(pb0[2], pb0[3], pb1[1]); PIN(rm); PIN(rm2); SBAR();
;             LDV(12); PVM(9); rm = max3f(rm, pb1[2], pb1[3]); rm2 = max3f(rm2, pb0[4], pb0[5]); PIN(rm); PIN(rm2); SBAR();
;             LDV(13); PVM(10); rm = max3f(rm, pb0[6], pb0[7]); rm2 = max3f(rm2, pb1[4], pb1[5]); PIN(rm); PIN(rm2); SBAR();
;             LDV(14); PVM(11); rm = max3f(rm, pb1[6], pb1[7]); rm2 = max3f(rm2, pb0[8], pb0[9]); PIN(rm); PIN(rm2); SBAR();
;             LDV(15); PVM(12); rm = max3f(rm, pb0[10], pb0[11]); rm2 = max3f(rm2, pb1[8], pb1[9]); PIN(rm); PIN(rm2); SBAR();
;             PVM(13); rm = max3f(rm, pb1[10], pb1[11]); rm2 = max3f(rm2, pb0[12], pb0[13]); PIN(rm); PIN(rm2); SBAR();
;             PVM(14); rm = max3f(rm, pb0[14], pb0[15]); rm2 = max3f(rm2, pb1[12], pb1[13]); PIN(rm); PIN(rm2); SBAR();
;             PVM(15); rm = max3f(rm, pb1[14], pb1[15]); PIN(rm); SBAR();
	ds_read2_b32 v[132:133], v192 offset1:1
	ds_read2_b32 v[134:135], v192 offset0:2 offset1:3
	ds_read2_b32 v[136:137], v192 offset0:8 offset1:9
	ds_read2_b32 v[138:139], v192 offset0:10 offset1:11
	ds_read2_b32 v[140:141], v192 offset0:16 offset1:17
	ds_read2_b32 v[142:143], v192 offset0:18 offset1:19
	ds_read2_b32 v[144:145], v192 offset0:24 offset1:25
	ds_read2_b32 v[146:147], v192 offset0:26 offset1:27
	ds_read2_b32 v[118:119], v192 offset0:32 offset1:33
	ds_read2_b32 v[120:121], v192 offset0:34 offset1:35
	ds_read2_b32 v[122:123], v192 offset0:40 offset1:41
	ds_read2_b32 v[164:165], v192 offset0:42 offset1:43
	s_waitcnt lgkmcnt(11)
	v_pk_add_f32 v[100:101], v[100:101], v[132:133]
	s_waitcnt lgkmcnt(5)
	v_pk_add_f32 v[112:113], v[112:113], v[144:145]
	v_pk_add_f32 v[110:111], v[110:111], v[142:143]
	v_pk_add_f32 v[108:109], v[108:109], v[140:141]
	ds_read2_b32 v[132:133], v192 offset0:48 offset1:49
	ds_read2_b32 v[140:141], v192 offset0:50 offset1:51
	ds_read2_b32 v[142:143], v192 offset0:56 offset1:57
	ds_read2_b32 v[144:145], v192 offset0:58 offset1:59
	s_waitcnt lgkmcnt(8)
	v_pk_add_f32 v[114:115], v[114:115], v[146:147]
	v_pk_add_f32 v[106:107], v[106:107], v[138:139]
	v_pk_add_f32 v[104:105], v[104:105], v[136:137]
	v_pk_add_f32 v[102:103], v[102:103], v[134:135]
	s_waitcnt lgkmcnt(7)
	v_pk_add_f32 v[84:85], v[84:85], v[118:119]
	s_waitcnt lgkmcnt(0)
	v_pk_add_f32 v[98:99], v[98:99], v[144:145]
	v_pk_add_f32 v[96:97], v[96:97], v[142:143]
	v_pk_add_f32 v[94:95], v[94:95], v[140:141]
	v_pk_add_f32 v[92:93], v[92:93], v[132:133]
	v_pk_add_f32 v[90:91], v[90:91], v[164:165]
	v_pk_add_f32 v[88:89], v[88:89], v[122:123]
	v_pk_add_f32 v[86:87], v[86:87], v[120:121]
.Lat2_405:
	s_waitcnt lgkmcnt(4)
	v_mfma_f32_32x32x16_bf16 v[68:83], v[172:175], v[124:127], v[68:83]
	s_cmp_eq_u32 s1, 0
	s_cbranch_scc1 .Lat2_nd2
	s_add_i32 m0, s16, s14
	s_nop 0
	global_load_lds_dwordx4 v[186:187], off
.Lat2_nd2:
	s_cmp_lt_u32 s3, s7
	s_cbranch_scc1 .Lat2_nomask
	v_mov_b32_e32 v100, v245
	v_mov_b32_e32 v101, v245
	v_mov_b32_e32 v102, v245
	v_mov_b32_e32 v103, v245
	v_mov_b32_e32 v104, v245
	v_mov_b32_e32 v105, v245
	v_mov_b32_e32 v106, v245
	v_mov_b32_e32 v107, v245
	v_mov_b32_e32 v108, v245
	v_mov_b32_e32 v109, v245
	v_mov_b32_e32 v110, v245
	v_mov_b32_e32 v111, v245
	v_mov_b32_e32 v112, v245
	v_mov_b32_e32 v113, v245
	v_mov_b32_e32 v114, v245
	v_mov_b32_e32 v115, v245
	v_mov_b32_e32 v84, v245
	v_mov_b32_e32 v85, v245
	v_mov_b32_e32 v86, v245
	v_mov_b32_e32 v87, v245
	v_mov_b32_e32 v88, v245
	v_mov_b32_e32 v89, v245
	v_mov_b32_e32 v90, v245
	v_mov_b32_e32 v91, v245
	v_mov_b32_e32 v92, v245
	v_mov_b32_e32 v93, v245
	v_mov_b32_e32 v94, v245
	v_mov_b32_e32 v95, v245
	v_mov_b32_e32 v96, v245
	v_mov_b32_e32 v97, v245
	v_mov_b32_e32 v98, v245
	v_mov_b32_e32 v99, v245
.Lat2_nomask:
	v_add_f32_e32 v197, v197, v116
	ds_read_b64_tr_b16 v[132:133], v190 offset:30720
	ds_read_b64_tr_b16 v[134:135], v190 offset:31232
	v_max3_f32 v116, v100, v101, v84
	v_max3_f32 v117, v102, v103, v85
	s_waitcnt lgkmcnt(4)
	v_mfma_f32_32x32x16_bf16 v[52:67], v[176:179], v[124:127], v[52:67]
	ds_read_b64_tr_b16 v[136:137], v190 offset:19456
	ds_read_b64_tr_b16 v[138:139], v190 offset:19968
	v_max3_f32 v116, v116, v86, v87
	v_max3_f32 v117, v117, v104, v105
	s_waitcnt lgkmcnt(4)
	v_mfma_f32_32x32x16_bf16 v[36:51], v[180:183], v[124:127], v[36:51]
	ds_read_b64_tr_b16 v[140:141], v190 offset:23552
	ds_read_b64_tr_b16 v[142:143], v190 offset:24064
	v_max3_f32 v116, v116, v106, v107
	v_max3_f32 v117, v117, v88, v89
	s_waitcnt lgkmcnt(4)
	v_mfma_f32_32x32x16_bf16 v[20:35], v[132:135], v[124:127], v[20:35]
	ds_read_b64_tr_b16 v[144:145], v190 offset:27648
	ds_read_b64_tr_b16 v[146:147], v190 offset:28160
	v_max3_f32 v116, v116, v90, v91
	v_max3_f32 v117, v117, v108, v109
	s_waitcnt lgkmcnt(4)
	v_mfma_f32_32x32x16_bf16 v[68:83], v[136:139], v[128:131], v[68:83]
	s_cmp_eq_u32 s1, 0
	s_cbranch_scc1 .Lat2_nd3
	s_add_i32 m0, s17, s14
	v_lshl_add_u64 v[214:215], v[186:187], 0, s[94:95]
	global_load_lds_dwordx4 v[214:215], off
; #define LAS __attribute__((address_space(3)))
; DI float max3f(float a, float b, float c) { float r; asm("v_max3_f32 %0, %1, %2, %3" : "=v"(r) : "v"(a), "v"(b), "v"(c)); return r; }
; DI float swapmax(float m) { auto rr = __builtin_amdgcn_permlane32_swap(__float_as_uint(m), __float_as_uint(m), false, false); return fmaxf(__uint_as_float(rr[0]), __uint_as_float(rr[1])); }
; DI float swapsum(float m) { auto rr = __builtin_amdgcn_permlane32_swap(__float_as_uint(m), __float_as_uint(m), false, false); return __uint_as_float(rr[0]) + __uint_as_float(rr[1]); }
; template <int KIND> DI void attn_unit(const Params& P, int b, int h, int qb, char* shm, float lam, bool dry = false) {
;     ...
;             PVM(13); rm = max3f(rm, pb1[10], pb1[11]); rm2 = max3f(rm2, pb0[12], pb0[13]); PIN(rm); PIN(rm2); SBAR();
;             PVM(14); rm = max3f(rm, pb0[14], pb0[15]); rm2 = max3f(rm2, pb1[12], pb1[13]); PIN(rm); PIN(rm2); SBAR();
;             PVM(15); rm = max3f(rm, pb1[14], pb1[15]); PIN(rm); SBAR();
;         } else {
;             LDV(7); PVM(4); rm = max3f(pb0[0], pb0[1], pb1[0]); rm2 = max3f(pb0[2], pb0[3], pb1[1]); rm = max3f(rm, pb1[2], pb1[3]); rm2 = max3f(rm2, pb0[4], pb0[5]); PIN(rm); PIN(rm2); SBAR();
;             PVM(5); rm = max3f(rm, pb0[6], pb0[7]); rm2 = max3f(rm2, pb1[4], pb1[5]); rm = max3f(rm, pb1[6], pb1[7]); rm2 = max3f(rm2, pb0[8], pb0[9]); PIN(rm); PIN(rm2); SBAR();
;             PVM(6); rm = max3f(rm, pb0[10], pb0[11]); rm2 = max3f(rm2, pb1[8], pb1[9]); rm = max3f(rm, pb1[10], pb1[11]); rm2 = max3f(rm2, pb0[12], pb0[13]); PIN(rm); PIN(rm2); SBAR();
;             PVM(7); rm = max3f(rm, pb0[14], pb0[15]); rm2 = max3f(rm2, pb1[12], pb1[13]); rm = max3f(rm, pb1[14], pb1[15]); PIN(rm); PIN(rm2); SBAR();
;         }
;     ...
;         rm = swapmax(max3f(rm, rm2, rm2));
;         if (KIND == 2) {
;             const u32x2 kx = *(const LAS u32x2*)(shm3 + sc + 32768);
;             const float xk0 = __uint_as_float(kx.x << 16) + __uint_as_float(kx.x & 0xffff0000u) + __uint_as_float(kx.y << 16);
;             const float ltot = swapsum(lsum);
;             const bool ok = (qkmax + cb + xk0) < (mhat + __builtin_amdgcn_logf(ltot) - 54.0f);
;             const bool allok = __all(ok) && !(ATT_TILE(i) > wt_hi);
;             if (lane == 0) vote[8 * (i & 3) + wid] = allok ? 1u : 0u;
;         }
;         if (i + 1 < nt_eff) ATT_DECIDE(pb0, pb1, rm);
.Lat2_nd3:
	ds_read_b64_tr_b16 v[132:133], v190 offset:31744
	ds_read_b64_tr_b16 v[134:135], v190 offset:32256
	v_max3_f32 v116, v116, v110, v111
	v_max3_f32 v117, v117, v92, v93
	s_waitcnt lgkmcnt(4)
	v_mfma_f32_32x32x16_bf16 v[52:67], v[140:143], v[128:131], v[52:67]
	v_max3_f32 v116, v116, v94, v95
	v_max3_f32 v117, v117, v112, v113
	s_waitcnt lgkmcnt(2)
	v_mfma_f32_32x32x16_bf16 v[36:51], v[144:147], v[128:131], v[36:51]
	v_max3_f32 v116, v116, v114, v115
	v_max3_f32 v117, v117, v96, v97
	s_waitcnt lgkmcnt(0)
	v_mfma_f32_32x32x16_bf16 v[20:35], v[132:135], v[128:131], v[20:35]
	v_max3_f32 v116, v116, v98, v99
	v_max3_f32 v116, v116, v117, v117
	s_add_i32 s3, s3, 1
	v_mov_b32_e32 v117, v116
	s_cmp_ge_u32 s3, s18
	s_nop 0
	v_permlane32_swap_b32_e32 v116, v117
	s_cbranch_scc1 .Lat2_408
	v_max_f32_e32 v116, v116, v116
	v_max_f32_e32 v117, v117, v117
	v_max_f32_e32 v116, v116, v117
	v_cmp_lt_f32_e32 vcc, s88, v116
	s_cbranch_vccz .Lat2_408
	v_max_f32_e32 v116, v116, v116
	v_max_f32_e32 v117, 0, v116
	v_exp_f32_e64 v116, -v117
	v_sub_f32_e32 v115, v115, v117
	v_sub_f32_e32 v114, v114, v117
	v_sub_f32_e32 v113, v113, v117
	v_pk_mul_f32 v[82:83], v[82:83], v[116:117] op_sel_hi:[1,0]
	v_pk_mul_f32 v[80:81], v[80:81], v[116:117] op_sel_hi:[1,0]
	v_pk_mul_f32 v[78:79], v[78:79], v[116:117] op_sel_hi:[1,0]
	v_pk_mul_f32 v[76:77], v[76:77], v[116:117] op_sel_hi:[1,0]
	v_pk_mul_f32 v[74:75], v[74:75], v[116:117] op_sel_hi:[1,0]
	v_pk_mul_f32 v[72:73], v[72:73], v[116:117] op_sel_hi:[1,0]
	v_pk_mul_f32 v[70:71], v[70:71], v[116:117] op_sel_hi:[1,0]
	v_pk_mul_f32 v[68:69], v[68:69], v[116:117] op_sel_hi:[1,0]
	v_pk_mul_f32 v[66:67], v[66:67], v[116:117] op_sel_hi:[1,0]
	v_pk_mul_f32 v[64:65], v[64:65], v[116:117] op_sel_hi:[1,0]
	v_pk_mul_f32 v[62:63], v[62:63], v[116:117] op_sel_hi:[1,0]
	v_pk_mul_f32 v[60:61], v[60:61], v[116:117] op_sel_hi:[1,0]
	v_pk_mul_f32 v[58:59], v[58:59], v[116:117] op_sel_hi:[1,0]
	v_pk_mul_f32 v[56:57], v[56:57], v[116:117] op_sel_hi:[1,0]
	v_pk_mul_f32 v[54:55], v[54:55], v[116:117] op_sel_hi:[1,0]
	v_pk_mul_f32 v[52:53], v[52:53], v[116:117] op_sel_hi:[1,0]
	v_pk_mul_f32 v[50:51], v[50:51], v[116:117] op_sel_hi:[1,0]
	v_pk_mul_f32 v[48:49], v[48:49], v[116:117] op_sel_hi:[1,0]
	v_pk_mul_f32 v[46:47], v[46:47], v[116:117] op_sel_hi:[1,0]
	v_pk_mul_f32 v[44:45], v[44:45], v[116:117] op_sel_hi:[1,0]
	v_pk_mul_f32 v[42:43], v[42:43], v[116:117] op_sel_hi:[1,0]
	v_pk_mul_f32 v[40:41], v[40:41], v[116:117] op_sel_hi:[1,0]
	v_pk_mul_f32 v[38:39], v[38:39], v[116:117] op_sel_hi:[1,0]
	v_pk_mul_f32 v[36:37], v[36:37], v[116:117] op_sel_hi:[1,0]
	v_pk_mul_f32 v[34:35], v[34:35], v[116:117] op_sel_hi:[1,0]
	v_pk_mul_f32 v[32:33], v[32:33], v[116:117] op_sel_hi:[1,0]
	v_pk_mul_f32 v[30:31], v[30:31], v[116:117] op_sel_hi:[1,0]
	v_pk_mul_f32 v[28:29], v[28:29], v[116:117] op_sel_hi:[1,0]
	v_pk_mul_f32 v[26:27], v[26:27], v[116:117] op_sel_hi:[1,0]
	v_pk_mul_f32 v[24:25], v[24:25], v[116:117] op_sel_hi:[1,0]
	v_pk_mul_f32 v[22:23], v[22:23], v[116:117] op_sel_hi:[1,0]
	v_pk_mul_f32 v[20:21], v[20:21], v[116:117] op_sel_hi:[1,0]
	v_sub_f32_e32 v112, v112, v117
	v_sub_f32_e32 v111, v111, v117
	v_sub_f32_e32 v110, v110, v117
	v_sub_f32_e32 v109, v109, v117
	v_sub_f32_e32 v108, v108, v117
	v_sub_f32_e32 v107, v107, v117
	v_sub_f32_e32 v106, v106, v117
	v_sub_f32_e32 v105, v105, v117
	v_sub_f32_e32 v104, v104, v117
	v_sub_f32_e32 v103, v103, v117
	v_sub_f32_e32 v102, v102, v117
	v_sub_f32_e32 v101, v101, v117
	v_sub_f32_e32 v100, v100, v117
	v_sub_f32_e32 v99, v99, v117
	v_sub_f32_e32 v98, v98, v117
	v_sub_f32_e32 v97, v97, v117
	v_sub_f32_e32 v96, v96, v117
	v_sub_f32_e32 v95, v95, v117
	v_sub_f32_e32 v94, v94, v117
	v_sub_f32_e32 v93, v93, v117
	v_sub_f32_e32 v92, v92, v117
	v_sub_f32_e32 v91, v91, v117
	v_sub_f32_e32 v90, v90, v117
	v_sub_f32_e32 v89, v89, v117
	v_sub_f32_e32 v88, v88, v117
	v_sub_f32_e32 v87, v87, v117
	v_sub_f32_e32 v86, v86, v117
	v_sub_f32_e32 v85, v85, v117
	v_sub_f32_e32 v84, v84, v117
	v_sub_f32_e32 v19, v19, v117
	v_sub_f32_e32 v18, v18, v117
	v_sub_f32_e32 v17, v17, v117
	v_sub_f32_e32 v16, v16, v117
	v_sub_f32_e32 v15, v15, v117
	v_sub_f32_e32 v14, v14, v117
	v_sub_f32_e32 v13, v13, v117
	v_sub_f32_e32 v12, v12, v117
	v_sub_f32_e32 v11, v11, v117
	v_sub_f32_e32 v10, v10, v117
	v_sub_f32_e32 v9, v9, v117
	v_sub_f32_e32 v8, v8, v117
	v_sub_f32_e32 v7, v7, v117
	v_sub_f32_e32 v6, v6, v117
	v_sub_f32_e32 v5, v5, v117
	v_sub_f32_e32 v4, v4, v117
	v_mul_f32_e32 v197, v197, v116

.LBB0_411:
	s_waitcnt vmcnt(4) lgkmcnt(0)
	s_barrier
	s_branch .LBB0_401
